# ssd_out epilogue: z rows of token blocks 1..3 requested up front (dummy loads)
# speedup vs baseline: 1.0051x; 1.0051x over previous
.LBB0_908:
	v_readlane_b32 s36, v241, 27
	v_readlane_b32 s37, v241, 28
	v_add_u32_e32 v130, 64, v141
	s_lshl_b32 s30, s56, 1
	v_lshl_add_u64 v[128:129], v[138:139], 2, s[36:37]
	global_load_dword v128, v[128:129], off
	v_xor_b32_e32 v129, 16, v188
	v_cmp_lt_i32_e32 vcc, v129, v130
	v_ashrrev_i32_e32 v137, 31, v136
	v_readlane_b32 s4, v239, 36
	v_cndmask_b32_e32 v129, v188, v129, vcc
	v_lshlrev_b32_e32 v151, 2, v129
	v_xor_b32_e32 v129, 32, v188
	v_cmp_lt_i32_e32 vcc, v129, v130
	v_lshl_add_u32 v133, v140, 2, s4
	s_mov_b64 s[4:5], 0x2000
	v_cndmask_b32_e32 v129, v188, v129, vcc
	v_lshlrev_b32_e32 v152, 2, v129
	v_mul_f32_e32 v129, 0x3fb8aa3b, v153
	v_exp_f32_e32 v132, v129
	v_mul_u32_u24_e32 v129, 0x1b00, v144
	v_lshlrev_b32_e32 v168, 1, v129
	v_lshl_add_u64 v[130:131], s[8:9], 0, v[168:169]
	v_lshl_add_u64 v[134:135], v[130:131], 0, s[30:31]
	v_lshl_add_u64 v[134:135], v[136:137], 1, v[134:135]
	v_lshlrev_b32_e32 v168, 1, v145
	v_lshl_add_u64 v[134:135], v[134:135], 0, v[168:169]
	v_lshl_add_u64 v[140:141], v[134:135], 0, s[4:5]
	v_add_co_u32_e32 v134, vcc, s75, v134
	v_mul_u32_u24_e32 v153, 0x420, v144
	s_nop 0
	v_addc_co_u32_e32 v135, vcc, 0, v135, vcc
	global_load_dwordx2 v[134:135], v[134:135], off
	v_mov_b32_e32 v252, 0x36000
	v_mov_b32_e32 v253, 0
	v_lshl_add_u64 v[248:249], v[140:141], 0, v[252:253]
	global_load_dword v254, v[248:249], off
	v_lshl_add_u64 v[250:251], v[248:249], 0, v[252:253]
	global_load_dword v254, v[250:251], off
	v_lshl_add_u64 v[248:249], v[250:251], 0, v[252:253]
	global_load_dword v255, v[248:249], off
	v_add3_u32 v129, v150, v153, v168
	ds_read2_b64 v[154:157], v129 offset1:4
	v_pk_fma_f32 v[94:95], v[132:133], v[126:127], v[94:95] op_sel_hi:[0,1,1]
	v_pk_fma_f32 v[90:91], v[132:133], v[122:123], v[90:91] op_sel_hi:[0,1,1]
	v_pk_fma_f32 v[92:93], v[132:133], v[124:125], v[92:93] op_sel_hi:[0,1,1]
	v_pk_fma_f32 v[78:79], v[132:133], v[118:119], v[78:79] op_sel_hi:[0,1,1]
	s_waitcnt lgkmcnt(0)
	v_lshlrev_b32_e32 v138, 16, v154
	v_and_b32_e32 v139, 0xffff0000, v154
	v_lshlrev_b32_e32 v154, 16, v155
	v_and_b32_e32 v155, 0xffff0000, v155
	v_pk_fma_f32 v[88:89], v[132:133], v[120:121], v[88:89] op_sel_hi:[0,1,1]
	v_pk_fma_f32 v[76:77], v[132:133], v[116:117], v[76:77] op_sel_hi:[0,1,1]
	v_pk_fma_f32 v[64:65], v[132:133], v[112:113], v[64:65] op_sel_hi:[0,1,1]
	v_pk_fma_f32 v[66:67], v[132:133], v[114:115], v[66:67] op_sel_hi:[0,1,1]
	v_readlane_b32 s38, v241, 29
	v_readlane_b32 s39, v241, 30
	v_readlane_b32 s40, v241, 31
	v_readlane_b32 s41, v241, 32
	v_readlane_b32 s42, v241, 33
	v_readlane_b32 s43, v241, 34
	v_readlane_b32 s44, v241, 35
	v_readlane_b32 s45, v241, 36
	v_readlane_b32 s46, v241, 37
	v_readlane_b32 s47, v241, 38
	v_readlane_b32 s48, v241, 39
	v_readlane_b32 s49, v241, 40
	v_readlane_b32 s50, v241, 41
	v_readlane_b32 s51, v241, 42
	global_load_dwordx2 v[118:119], v[140:141], off offset:96
	s_waitcnt vmcnt(2)
	v_pk_fma_f32 v[94:95], v[128:129], v[154:155], v[94:95] op_sel_hi:[0,1,1]
	v_lshlrev_b32_e32 v154, 16, v157
	v_and_b32_e32 v155, 0xffff0000, v157
	v_pk_fma_f32 v[90:91], v[128:129], v[154:155], v[90:91] op_sel_hi:[0,1,1]
	global_load_dwordx2 v[154:155], v[140:141], off offset:64
	v_pk_fma_f32 v[92:93], v[128:129], v[138:139], v[92:93] op_sel_hi:[0,1,1]
	s_waitcnt vmcnt(2)
	v_lshlrev_b32_e32 v158, 16, v134
	v_and_b32_e32 v159, 0xffff0000, v134
	v_lshlrev_b32_e32 v134, 16, v135
	v_and_b32_e32 v135, 0xffff0000, v135
	v_mul_f32_e32 v138, 0xbfb8aa3b, v134
	v_pk_mul_f32 v[94:95], v[94:95], v[134:135]
	v_mul_f32_e32 v126, 0xbfb8aa3b, v135
	global_load_dwordx2 v[134:135], v[140:141], off offset:32
	v_exp_f32_e32 v138, v138
	v_exp_f32_e32 v126, v126
	v_mul_f32_e32 v160, 0xbfb8aa3b, v158
	v_pk_mul_f32 v[92:93], v[92:93], v[158:159]
	v_add_f32_e32 v138, 1.0, v138
	v_add_f32_e32 v126, 1.0, v126
	v_rcp_f32_e32 v138, v138
	v_rcp_f32_e32 v139, v126
	v_mul_f32_e32 v124, 0xbfb8aa3b, v159
	v_exp_f32_e32 v160, v160
	v_exp_f32_e32 v124, v124
	v_pk_mul_f32 v[94:95], v[94:95], v[138:139]
	v_lshlrev_b32_e32 v138, 16, v156
	v_and_b32_e32 v139, 0xffff0000, v156
	v_pk_fma_f32 v[88:89], v[128:129], v[138:139], v[88:89] op_sel_hi:[0,1,1]
	v_add_f32_e32 v160, 1.0, v160
	v_add_f32_e32 v124, 1.0, v124
	v_rcp_f32_e32 v160, v160
	v_rcp_f32_e32 v161, v124
	v_pk_mul_f32 v[126:127], v[94:95], v[94:95]
	v_pk_mul_f32 v[92:93], v[92:93], v[160:161]
	s_nop 0
	v_pk_mul_f32 v[124:125], v[92:93], v[92:93]
	s_waitcnt vmcnt(0)
	v_lshlrev_b32_e32 v156, 16, v134
	v_and_b32_e32 v157, 0xffff0000, v134
	v_mul_f32_e32 v134, 0xbfb8aa3b, v156
	v_mul_f32_e32 v120, 0xbfb8aa3b, v157
	v_exp_f32_e32 v134, v134
	v_exp_f32_e32 v120, v120
	v_lshlrev_b32_e32 v158, 16, v135
	v_and_b32_e32 v159, 0xffff0000, v135
	v_add_f32_e32 v134, 1.0, v134
	v_add_f32_e32 v120, 1.0, v120
	v_rcp_f32_e32 v134, v134
	v_rcp_f32_e32 v135, v120
	v_pk_mul_f32 v[88:89], v[88:89], v[156:157]
	v_pk_mul_f32 v[90:91], v[90:91], v[158:159]
	v_add_f32_e32 v114, v124, v125
	v_pk_mul_f32 v[120:121], v[88:89], v[134:135]
	v_mul_f32_e32 v88, 0xbfb8aa3b, v158
	v_mul_f32_e32 v89, 0xbfb8aa3b, v159
	v_exp_f32_e32 v88, v88
	v_exp_f32_e32 v89, v89
	v_add_f32_e32 v114, v114, v126
	v_pk_mul_f32 v[134:135], v[120:121], v[120:121]
	v_add_f32_e32 v88, 1.0, v88
	v_add_f32_e32 v89, 1.0, v89
	v_rcp_f32_e32 v88, v88
	v_rcp_f32_e32 v89, v89
	v_add_f32_e32 v114, v127, v114
	v_add_f32_e32 v114, v114, v134
	v_add_f32_e32 v114, v135, v114
	v_pk_mul_f32 v[122:123], v[90:91], v[88:89]
	ds_read2_b64 v[88:91], v129 offset0:8 offset1:12
	v_pk_mul_f32 v[138:139], v[122:123], v[122:123]
	s_waitcnt lgkmcnt(0)
	v_lshlrev_b32_e32 v156, 16, v88
	v_and_b32_e32 v157, 0xffff0000, v88
	v_lshlrev_b32_e32 v88, 16, v154
	v_mul_f32_e32 v129, 0xbfb8aa3b, v88
	v_exp_f32_e32 v129, v129
	v_lshlrev_b32_e32 v158, 16, v89
	v_and_b32_e32 v159, 0xffff0000, v89
	v_and_b32_e32 v89, 0xffff0000, v154
	v_add_f32_e32 v129, 1.0, v129
	v_lshlrev_b32_e32 v154, 16, v155
	v_and_b32_e32 v155, 0xffff0000, v155
	v_pk_fma_f32 v[78:79], v[128:129], v[158:159], v[78:79] op_sel_hi:[0,1,1]
	v_mul_f32_e32 v116, 0xbfb8aa3b, v154
	v_pk_mul_f32 v[78:79], v[78:79], v[154:155]
	v_lshlrev_b32_e32 v154, 16, v118
	v_rcp_f32_e32 v160, v129
	v_pk_fma_f32 v[76:77], v[128:129], v[156:157], v[76:77] op_sel_hi:[0,1,1]
	v_mul_f32_e32 v129, 0xbfb8aa3b, v154
	v_exp_f32_e32 v129, v129
	v_mul_f32_e32 v117, 0xbfb8aa3b, v155
	v_lshlrev_b32_e32 v140, 16, v90
	v_and_b32_e32 v141, 0xffff0000, v90
	v_and_b32_e32 v155, 0xffff0000, v118
	v_lshlrev_b32_e32 v118, 16, v119
	v_add_f32_e32 v129, 1.0, v129
	v_pk_mul_f32 v[76:77], v[76:77], v[88:89]
	v_mul_f32_e32 v88, 0xbfb8aa3b, v89
	v_rcp_f32_e32 v156, v129
	v_pk_fma_f32 v[64:65], v[128:129], v[140:141], v[64:65] op_sel_hi:[0,1,1]
	v_mul_f32_e32 v129, 0xbfb8aa3b, v118
	v_exp_f32_e32 v88, v88
	v_exp_f32_e32 v129, v129
	v_exp_f32_e32 v116, v116
	v_exp_f32_e32 v117, v117
	v_mul_f32_e32 v112, 0xbfb8aa3b, v155
	v_add_f32_e32 v88, 1.0, v88
	v_lshlrev_b32_e32 v90, 16, v91
	v_and_b32_e32 v91, 0xffff0000, v91
	v_and_b32_e32 v119, 0xffff0000, v119
	v_exp_f32_e32 v112, v112
	v_add_f32_e32 v129, 1.0, v129
	v_rcp_f32_e32 v161, v88
	v_pk_fma_f32 v[66:67], v[128:129], v[90:91], v[66:67] op_sel_hi:[0,1,1]
	v_mul_f32_e32 v90, 0xbfb8aa3b, v119
	v_add_f32_e32 v116, 1.0, v116
	v_add_f32_e32 v117, 1.0, v117
	v_exp_f32_e32 v90, v90
	v_rcp_f32_e32 v116, v116
	v_rcp_f32_e32 v117, v117
	v_add_f32_e32 v112, 1.0, v112
	v_pk_mul_f32 v[76:77], v[76:77], v[160:161]
	v_rcp_f32_e32 v157, v112
	v_add_f32_e32 v114, v138, v114
	v_pk_mul_f32 v[88:89], v[76:77], v[76:77]
	v_add_f32_e32 v90, 1.0, v90
	v_add_f32_e32 v114, v139, v114
	v_pk_mul_f32 v[78:79], v[78:79], v[116:117]
	v_rcp_f32_e32 v140, v129
	v_rcp_f32_e32 v141, v90
	v_add_f32_e32 v88, v114, v88
	v_pk_mul_f32 v[116:117], v[78:79], v[78:79]
	v_pk_mul_f32 v[64:65], v[64:65], v[154:155]
	v_add_f32_e32 v88, v89, v88
	v_pk_mul_f32 v[64:65], v[64:65], v[156:157]
	v_add_f32_e32 v88, v116, v88
	v_pk_mul_f32 v[112:113], v[64:65], v[64:65]
	v_pk_mul_f32 v[66:67], v[66:67], v[118:119]
	v_add_f32_e32 v88, v117, v88
	v_pk_mul_f32 v[66:67], v[66:67], v[140:141]
	v_add_f32_e32 v88, v88, v112
	v_pk_mul_f32 v[90:91], v[66:67], v[66:67]
	v_add_f32_e32 v88, v113, v88
	v_add_f32_e32 v88, v90, v88
	v_add_f32_e32 v88, v91, v88
	ds_bpermute_b32 v89, v151, v88
	s_waitcnt lgkmcnt(0)
	v_add_f32_e32 v88, v88, v89
	ds_bpermute_b32 v89, v152, v88
	s_and_saveexec_b64 s[4:5], s[2:3]
	s_cbranch_execz .LBB0_910
	v_lshl_add_u32 v90, v144, 5, v133
	s_waitcnt lgkmcnt(0)
	v_add_f32_e32 v88, v88, v89
	ds_write_b32 v90, v88
